# final stack plus P16 sample-row path: the 8 PUP row loads issued first (before the split-K slab loads) into spare registers, copied into place later; removes one memory round trip from the kernel's la
# baseline (speedup 1.0000x reference)
; #define GAS __attribute__((address_space(1)))
; __device__ __forceinline__ float bflo(unsigned w) { return __uint_as_float(w << 16); }
; __device__ __forceinline__ float bfhi(unsigned w) { return __uint_as_float(w & 0xffff0000u); }
; __device__ __forceinline__ float sigmf(float x) { return __builtin_amdgcn_rcpf(1.0f + __expf(-x)); }
;     ...
;             if (TSRC != 0 && r >= NP) {
;                 const GAS f32x4* sp = (const GAS f32x4*)(WSP(float, WS_SLAB) + (size_t)(r - NP) * D) + lane;
; #pragma unroll
;                 for (int j = 0; j < 8; ++j) t[j] = sp[64 * j];
;                 _Pragma("unroll 1") for (int s = 1; s < nslab; ++s) { sp += (size_t)NS * D / 4;
; #pragma unroll
;                     for (int j = 0; j < 8; ++j) t[j] += sp[64 * j]; }
;                 if (TSRC == 2) { const GAS v2u* pp = (const GAS v2u*)(PUP + (size_t)r * D) + lane;
; #pragma unroll
;                     for (int j = 0; j < 8; ++j) { const v2u pw = pp[64 * j]; const f32x4 p = (f32x4){bflo(pw.x), bfhi(pw.x), bflo(pw.y), bfhi(pw.y)}; t[j] = (f32x4){sigmf(t[j][0]), sigmf(t[j][1]), sigmf(t[j][2]), sigmf(t[j][3])} * p; } }
.LBB0_1901:
	s_andn2_b64 vcc, exec, s[0:1]
	s_cbranch_vccnz .LBB0_1898
	v_lshl_add_u64 v[252:253], s[6:7], 1, v[72:73]
	global_load_dwordx2 v[234:235], v[252:253], off
	global_load_dwordx2 v[236:237], v[252:253], off offset:512
	global_load_dwordx2 v[238:239], v[252:253], off offset:1024
	global_load_dwordx2 v[240:241], v[252:253], off offset:1536
	global_load_dwordx2 v[242:243], v[252:253], off offset:2048
	global_load_dwordx2 v[246:247], v[252:253], off offset:2560
	global_load_dwordx2 v[248:249], v[252:253], off offset:3072
	global_load_dwordx2 v[250:251], v[252:253], off offset:3584
	s_add_i32 s0, s2, 0xffffe000
	s_mov_b32 s1, s5
	s_lshl_b64 s[0:1], s[0:1], 13
	v_lshl_add_u64 v[32:33], v[70:71], 0, s[0:1]
	v_add_co_u32_e32 v90, vcc, 0x1000, v32
	global_load_dwordx4 v[60:63], v[32:33], off
	global_load_dwordx4 v[56:59], v[32:33], off offset:1024
	global_load_dwordx4 v[52:55], v[32:33], off offset:2048
	global_load_dwordx4 v[48:51], v[32:33], off offset:3072
	v_addc_co_u32_e32 v91, vcc, 0, v33, vcc
	global_load_dwordx4 v[44:47], v[90:91], off
	global_load_dwordx4 v[40:43], v[90:91], off offset:1024
	global_load_dwordx4 v[36:39], v[90:91], off offset:2048
	global_load_dwordx4 v[32:35], v[90:91], off offset:3072
	s_lshl_b64 s[0:1], s[4:5], 13
	v_lshl_add_u64 v[90:91], v[68:69], 0, s[0:1]
	s_mov_b64 s[0:1], 0
.LBB0_1903:
	v_lshl_add_u64 v[106:107], v[90:91], 0, s[0:1]
	v_add_co_u32_e32 v122, vcc, s9, v106
	s_add_u32 s0, s0, 0x400000
	s_nop 0
	v_addc_co_u32_e32 v123, vcc, 0, v107, vcc
	v_add_co_u32_e32 v134, vcc, s10, v106
	s_addc_u32 s1, s1, 0
	s_nop 0
	v_addc_co_u32_e32 v135, vcc, 0, v107, vcc
	global_load_dwordx4 v[106:109], v[134:135], off offset:-4096
	global_load_dwordx4 v[110:113], v[122:123], off offset:1024
	global_load_dwordx4 v[114:117], v[122:123], off offset:2048
	global_load_dwordx4 v[118:121], v[122:123], off offset:3072
	s_nop 0
	global_load_dwordx4 v[122:125], v[134:135], off
	global_load_dwordx4 v[126:129], v[134:135], off offset:1024
	global_load_dwordx4 v[130:133], v[134:135], off offset:2048
	s_nop 0
	global_load_dwordx4 v[134:137], v[134:135], off offset:3072
	v_lshl_add_u64 v[138:139], v[90:91], 0, s[0:1]
	v_add_co_u32_e32 v154, vcc, s9, v138
	s_add_u32 s0, s0, 0x400000
	s_nop 0
	v_addc_co_u32_e32 v155, vcc, 0, v139, vcc
	v_add_co_u32_e32 v166, vcc, s10, v138
	s_addc_u32 s1, s1, 0
	s_nop 0
	v_addc_co_u32_e32 v167, vcc, 0, v139, vcc
	global_load_dwordx4 v[138:141], v[166:167], off offset:-4096
	global_load_dwordx4 v[142:145], v[154:155], off offset:1024
	global_load_dwordx4 v[146:149], v[154:155], off offset:2048
	global_load_dwordx4 v[150:153], v[154:155], off offset:3072
	s_nop 0
	global_load_dwordx4 v[154:157], v[166:167], off
	global_load_dwordx4 v[158:161], v[166:167], off offset:1024
	global_load_dwordx4 v[162:165], v[166:167], off offset:2048
	s_nop 0
	global_load_dwordx4 v[166:169], v[166:167], off offset:3072
	v_lshl_add_u64 v[170:171], v[90:91], 0, s[0:1]
	v_add_co_u32_e32 v186, vcc, s9, v170
	s_add_u32 s0, s0, 0x400000
	s_nop 0
	v_addc_co_u32_e32 v187, vcc, 0, v171, vcc
	v_add_co_u32_e32 v198, vcc, s10, v170
	s_addc_u32 s1, s1, 0
	s_nop 0
	v_addc_co_u32_e32 v199, vcc, 0, v171, vcc
	global_load_dwordx4 v[170:173], v[198:199], off offset:-4096
	global_load_dwordx4 v[174:177], v[186:187], off offset:1024
	global_load_dwordx4 v[178:181], v[186:187], off offset:2048
	global_load_dwordx4 v[182:185], v[186:187], off offset:3072
	s_nop 0
	global_load_dwordx4 v[186:189], v[198:199], off
	global_load_dwordx4 v[190:193], v[198:199], off offset:1024
	global_load_dwordx4 v[194:197], v[198:199], off offset:2048
	s_nop 0
	global_load_dwordx4 v[198:201], v[198:199], off offset:3072
	v_lshl_add_u64 v[202:203], v[90:91], 0, s[0:1]
	v_add_co_u32_e32 v218, vcc, s9, v202
	s_add_u32 s0, s0, 0x400000
	s_nop 0
	v_addc_co_u32_e32 v219, vcc, 0, v203, vcc
	v_add_co_u32_e32 v230, vcc, s10, v202
	s_addc_u32 s1, s1, 0
	s_nop 0
	v_addc_co_u32_e32 v231, vcc, 0, v203, vcc
	global_load_dwordx4 v[202:205], v[230:231], off offset:-4096
	global_load_dwordx4 v[206:209], v[218:219], off offset:1024
	global_load_dwordx4 v[210:213], v[218:219], off offset:2048
	global_load_dwordx4 v[214:217], v[218:219], off offset:3072
	s_nop 0
	global_load_dwordx4 v[218:221], v[230:231], off
	global_load_dwordx4 v[222:225], v[230:231], off offset:1024
	global_load_dwordx4 v[226:229], v[230:231], off offset:2048
	s_nop 0
	global_load_dwordx4 v[230:233], v[230:231], off offset:3072
	s_waitcnt vmcnt(24)
	v_pk_add_f32 v[62:63], v[62:63], v[108:109]
	v_pk_add_f32 v[60:61], v[60:61], v[106:107]
	v_pk_add_f32 v[58:59], v[58:59], v[112:113]
	v_pk_add_f32 v[56:57], v[56:57], v[110:111]
	v_pk_add_f32 v[54:55], v[54:55], v[116:117]
	v_pk_add_f32 v[52:53], v[52:53], v[114:115]
	v_pk_add_f32 v[50:51], v[50:51], v[120:121]
	v_pk_add_f32 v[48:49], v[48:49], v[118:119]
	v_pk_add_f32 v[46:47], v[46:47], v[124:125]
	v_pk_add_f32 v[44:45], v[44:45], v[122:123]
	v_pk_add_f32 v[42:43], v[42:43], v[128:129]
	v_pk_add_f32 v[40:41], v[40:41], v[126:127]
	v_pk_add_f32 v[38:39], v[38:39], v[132:133]
	v_pk_add_f32 v[36:37], v[36:37], v[130:131]
	v_pk_add_f32 v[34:35], v[34:35], v[136:137]
	v_pk_add_f32 v[32:33], v[32:33], v[134:135]
	v_lshl_add_u64 v[106:107], v[90:91], 0, s[0:1]
	v_add_co_u32_e32 v122, vcc, s9, v106
	s_add_u32 s0, s0, 0x400000
	s_nop 0
	v_addc_co_u32_e32 v123, vcc, 0, v107, vcc
	v_add_co_u32_e32 v134, vcc, s10, v106
	s_addc_u32 s1, s1, 0
	s_nop 0
	v_addc_co_u32_e32 v135, vcc, 0, v107, vcc
	global_load_dwordx4 v[106:109], v[134:135], off offset:-4096
	global_load_dwordx4 v[110:113], v[122:123], off offset:1024
	global_load_dwordx4 v[114:117], v[122:123], off offset:2048
	global_load_dwordx4 v[118:121], v[122:123], off offset:3072
	s_nop 0
	global_load_dwordx4 v[122:125], v[134:135], off
	global_load_dwordx4 v[126:129], v[134:135], off offset:1024
	global_load_dwordx4 v[130:133], v[134:135], off offset:2048
	s_nop 0
	global_load_dwordx4 v[134:137], v[134:135], off offset:3072
	s_waitcnt vmcnt(24)
; #define GAS __attribute__((address_space(1)))
;     ...
;                 const GAS f32x4* sp = (const GAS f32x4*)(WSP(float, WS_SLAB) + (size_t)(r - NP) * D) + lane;
; #pragma unroll
;                 for (int j = 0; j < 8; ++j) t[j] = sp[64 * j];
;                 _Pragma("unroll 1") for (int s = 1; s < nslab; ++s) { sp += (size_t)NS * D / 4;
; #pragma unroll
;                     for (int j = 0; j < 8; ++j) t[j] += sp[64 * j]; }
	v_pk_add_f32 v[62:63], v[62:63], v[140:141]
	v_pk_add_f32 v[60:61], v[60:61], v[138:139]
	v_pk_add_f32 v[58:59], v[58:59], v[144:145]
	v_pk_add_f32 v[56:57], v[56:57], v[142:143]
	v_pk_add_f32 v[54:55], v[54:55], v[148:149]
	v_pk_add_f32 v[52:53], v[52:53], v[146:147]
	v_pk_add_f32 v[50:51], v[50:51], v[152:153]
	v_pk_add_f32 v[48:49], v[48:49], v[150:151]
	v_pk_add_f32 v[46:47], v[46:47], v[156:157]
	v_pk_add_f32 v[44:45], v[44:45], v[154:155]
	v_pk_add_f32 v[42:43], v[42:43], v[160:161]
	v_pk_add_f32 v[40:41], v[40:41], v[158:159]
	v_pk_add_f32 v[38:39], v[38:39], v[164:165]
	v_pk_add_f32 v[36:37], v[36:37], v[162:163]
	v_pk_add_f32 v[34:35], v[34:35], v[168:169]
	v_pk_add_f32 v[32:33], v[32:33], v[166:167]
	v_lshl_add_u64 v[138:139], v[90:91], 0, s[0:1]
	v_add_co_u32_e32 v154, vcc, s9, v138
	s_add_u32 s0, s0, 0x400000
	s_nop 0
	v_addc_co_u32_e32 v155, vcc, 0, v139, vcc
	v_add_co_u32_e32 v166, vcc, s10, v138
	s_addc_u32 s1, s1, 0
	s_nop 0
	v_addc_co_u32_e32 v167, vcc, 0, v139, vcc
	global_load_dwordx4 v[138:141], v[166:167], off offset:-4096
	global_load_dwordx4 v[142:145], v[154:155], off offset:1024
	global_load_dwordx4 v[146:149], v[154:155], off offset:2048
	global_load_dwordx4 v[150:153], v[154:155], off offset:3072
	s_nop 0
	global_load_dwordx4 v[154:157], v[166:167], off
	global_load_dwordx4 v[158:161], v[166:167], off offset:1024
	global_load_dwordx4 v[162:165], v[166:167], off offset:2048
	s_nop 0
	global_load_dwordx4 v[166:169], v[166:167], off offset:3072
	s_waitcnt vmcnt(24)
	v_pk_add_f32 v[62:63], v[62:63], v[172:173]
	v_pk_add_f32 v[60:61], v[60:61], v[170:171]
	v_pk_add_f32 v[58:59], v[58:59], v[176:177]
	v_pk_add_f32 v[56:57], v[56:57], v[174:175]
	v_pk_add_f32 v[54:55], v[54:55], v[180:181]
	v_pk_add_f32 v[52:53], v[52:53], v[178:179]
	v_pk_add_f32 v[50:51], v[50:51], v[184:185]
	v_pk_add_f32 v[48:49], v[48:49], v[182:183]
	v_pk_add_f32 v[46:47], v[46:47], v[188:189]
	v_pk_add_f32 v[44:45], v[44:45], v[186:187]
	v_pk_add_f32 v[42:43], v[42:43], v[192:193]
	v_pk_add_f32 v[40:41], v[40:41], v[190:191]
	v_pk_add_f32 v[38:39], v[38:39], v[196:197]
	v_pk_add_f32 v[36:37], v[36:37], v[194:195]
	v_pk_add_f32 v[34:35], v[34:35], v[200:201]
	v_pk_add_f32 v[32:33], v[32:33], v[198:199]
	v_lshl_add_u64 v[170:171], v[90:91], 0, s[0:1]
	v_add_co_u32_e32 v186, vcc, s9, v170
	s_add_u32 s0, s0, 0x400000
	s_nop 0
	v_addc_co_u32_e32 v187, vcc, 0, v171, vcc
	v_add_co_u32_e32 v198, vcc, s10, v170
	s_addc_u32 s1, s1, 0
	s_nop 0
	v_addc_co_u32_e32 v199, vcc, 0, v171, vcc
	global_load_dwordx4 v[170:173], v[198:199], off offset:-4096
	global_load_dwordx4 v[174:177], v[186:187], off offset:1024
	global_load_dwordx4 v[178:181], v[186:187], off offset:2048
	global_load_dwordx4 v[182:185], v[186:187], off offset:3072
	s_nop 0
	global_load_dwordx4 v[186:189], v[198:199], off
	global_load_dwordx4 v[190:193], v[198:199], off offset:1024
	global_load_dwordx4 v[194:197], v[198:199], off offset:2048
	s_nop 0
	global_load_dwordx4 v[198:201], v[198:199], off offset:3072
	s_waitcnt vmcnt(24)
	v_pk_add_f32 v[62:63], v[62:63], v[204:205]
	v_pk_add_f32 v[60:61], v[60:61], v[202:203]
	v_pk_add_f32 v[58:59], v[58:59], v[208:209]
	v_pk_add_f32 v[56:57], v[56:57], v[206:207]
	v_pk_add_f32 v[54:55], v[54:55], v[212:213]
	v_pk_add_f32 v[52:53], v[52:53], v[210:211]
	v_pk_add_f32 v[50:51], v[50:51], v[216:217]
	v_pk_add_f32 v[48:49], v[48:49], v[214:215]
	v_pk_add_f32 v[46:47], v[46:47], v[220:221]
	v_pk_add_f32 v[44:45], v[44:45], v[218:219]
	v_pk_add_f32 v[42:43], v[42:43], v[224:225]
	v_pk_add_f32 v[40:41], v[40:41], v[222:223]
	v_pk_add_f32 v[38:39], v[38:39], v[228:229]
	v_pk_add_f32 v[36:37], v[36:37], v[226:227]
	v_pk_add_f32 v[34:35], v[34:35], v[232:233]
	v_pk_add_f32 v[32:33], v[32:33], v[230:231]
	s_waitcnt vmcnt(16)
	v_pk_add_f32 v[62:63], v[62:63], v[108:109]
	v_pk_add_f32 v[60:61], v[60:61], v[106:107]
	v_pk_add_f32 v[58:59], v[58:59], v[112:113]
	v_pk_add_f32 v[56:57], v[56:57], v[110:111]
	v_pk_add_f32 v[54:55], v[54:55], v[116:117]
	v_pk_add_f32 v[52:53], v[52:53], v[114:115]
	v_pk_add_f32 v[50:51], v[50:51], v[120:121]
	v_pk_add_f32 v[48:49], v[48:49], v[118:119]
	v_pk_add_f32 v[46:47], v[46:47], v[124:125]
	v_pk_add_f32 v[44:45], v[44:45], v[122:123]
	v_pk_add_f32 v[42:43], v[42:43], v[128:129]
	v_pk_add_f32 v[40:41], v[40:41], v[126:127]
	v_pk_add_f32 v[38:39], v[38:39], v[132:133]
	v_pk_add_f32 v[36:37], v[36:37], v[130:131]
	v_pk_add_f32 v[34:35], v[34:35], v[136:137]
	v_pk_add_f32 v[32:33], v[32:33], v[134:135]
	s_waitcnt vmcnt(8)
	v_pk_add_f32 v[62:63], v[62:63], v[140:141]
	v_pk_add_f32 v[60:61], v[60:61], v[138:139]
	v_pk_add_f32 v[58:59], v[58:59], v[144:145]
	v_pk_add_f32 v[56:57], v[56:57], v[142:143]
	v_pk_add_f32 v[54:55], v[54:55], v[148:149]
	v_pk_add_f32 v[52:53], v[52:53], v[146:147]
	v_pk_add_f32 v[50:51], v[50:51], v[152:153]
	v_pk_add_f32 v[48:49], v[48:49], v[150:151]
	v_pk_add_f32 v[46:47], v[46:47], v[156:157]
	v_pk_add_f32 v[44:45], v[44:45], v[154:155]
	v_pk_add_f32 v[42:43], v[42:43], v[160:161]
	v_pk_add_f32 v[40:41], v[40:41], v[158:159]
	v_pk_add_f32 v[38:39], v[38:39], v[164:165]
	v_pk_add_f32 v[36:37], v[36:37], v[162:163]
	v_pk_add_f32 v[34:35], v[34:35], v[168:169]
	v_pk_add_f32 v[32:33], v[32:33], v[166:167]
	s_waitcnt vmcnt(0)
; #define GAS __attribute__((address_space(1)))
; __device__ __forceinline__ float bflo(unsigned w) { return __uint_as_float(w << 16); }
; __device__ __forceinline__ float bfhi(unsigned w) { return __uint_as_float(w & 0xffff0000u); }
; __device__ __forceinline__ float sigmf(float x) { return __builtin_amdgcn_rcpf(1.0f + __expf(-x)); }
; __device__ __forceinline__ float dot4(f32x4 a, f32x4 b) { return (a[0] * b[0] + a[1] * b[1]) + (a[2] * b[2] + a[3] * b[3]); }
;     ...
;                 _Pragma("unroll 1") for (int s = 1; s < nslab; ++s) { sp += (size_t)NS * D / 4;
; #pragma unroll
;                     for (int j = 0; j < 8; ++j) t[j] += sp[64 * j]; }
;                 if (TSRC == 2) { const GAS v2u* pp = (const GAS v2u*)(PUP + (size_t)r * D) + lane;
; #pragma unroll
;                     for (int j = 0; j < 8; ++j) { const v2u pw = pp[64 * j]; const f32x4 p = (f32x4){bflo(pw.x), bfhi(pw.x), bflo(pw.y), bfhi(pw.y)}; t[j] = (f32x4){sigmf(t[j][0]), sigmf(t[j][1]), sigmf(t[j][2]), sigmf(t[j][3])} * p; } }
; #pragma unroll
;                 for (int j = 0; j < 8; ++j) ss += dot4(t[j], t[j]);
	v_pk_add_f32 v[62:63], v[62:63], v[172:173]
	v_pk_add_f32 v[60:61], v[60:61], v[170:171]
	v_pk_add_f32 v[58:59], v[58:59], v[176:177]
	v_pk_add_f32 v[56:57], v[56:57], v[174:175]
	v_pk_add_f32 v[54:55], v[54:55], v[180:181]
	v_pk_add_f32 v[52:53], v[52:53], v[178:179]
	v_pk_add_f32 v[50:51], v[50:51], v[184:185]
	v_pk_add_f32 v[48:49], v[48:49], v[182:183]
	v_pk_add_f32 v[46:47], v[46:47], v[188:189]
	v_pk_add_f32 v[44:45], v[44:45], v[186:187]
	v_pk_add_f32 v[42:43], v[42:43], v[192:193]
	v_pk_add_f32 v[40:41], v[40:41], v[190:191]
	v_pk_add_f32 v[38:39], v[38:39], v[196:197]
	v_pk_add_f32 v[36:37], v[36:37], v[194:195]
	v_pk_add_f32 v[34:35], v[34:35], v[200:201]
	v_pk_add_f32 v[32:33], v[32:33], v[198:199]
	s_cmp_eq_u32 s0, 0x1c00000
	v_lshl_add_u64 v[90:91], s[6:7], 1, v[72:73]
	v_mov_b32_e32 v106, v234
	v_mov_b32_e32 v107, v235
	v_mov_b32_e32 v108, v236
	v_mov_b32_e32 v109, v237
	v_mov_b32_e32 v110, v238
	v_mov_b32_e32 v111, v239
	v_mov_b32_e32 v112, v240
	v_mov_b32_e32 v113, v241
	v_mov_b32_e32 v114, v242
	v_mov_b32_e32 v115, v243
	v_mov_b32_e32 v116, v246
	v_mov_b32_e32 v117, v247
	v_mov_b32_e32 v118, v248
	v_mov_b32_e32 v119, v249
	v_mul_f32_e32 v56, 0xbfb8aa3b, v56
	v_mov_b32_e32 v90, v250
	v_mov_b32_e32 v91, v251
	v_mul_f32_e32 v57, 0xbfb8aa3b, v57
	v_mul_f32_e32 v58, 0xbfb8aa3b, v58
	v_mul_f32_e32 v59, 0xbfb8aa3b, v59
	v_mul_f32_e32 v54, 0xbfb8aa3b, v54
	v_mul_f32_e32 v55, 0xbfb8aa3b, v55
	v_exp_f32_e32 v56, v56
	v_exp_f32_e32 v57, v57
	v_exp_f32_e32 v58, v58
	v_exp_f32_e32 v59, v59
	v_exp_f32_e32 v54, v54
	v_exp_f32_e32 v55, v55
	v_mul_f32_e32 v60, 0xbfb8aa3b, v60
	v_mul_f32_e32 v61, 0xbfb8aa3b, v61
	v_mul_f32_e32 v62, 0xbfb8aa3b, v62
	v_mul_f32_e32 v63, 0xbfb8aa3b, v63
	v_mul_f32_e32 v52, 0xbfb8aa3b, v52
	v_mul_f32_e32 v53, 0xbfb8aa3b, v53
	v_mul_f32_e32 v105, 0xbfb8aa3b, v49
	v_exp_f32_e32 v49, v60
	v_exp_f32_e32 v60, v61
	v_exp_f32_e32 v61, v62
	v_exp_f32_e32 v62, v63
	v_exp_f32_e32 v52, v52
	v_exp_f32_e32 v53, v53
	v_add_f32_e32 v56, 1.0, v56
	v_add_f32_e32 v57, 1.0, v57
	v_add_f32_e32 v58, 1.0, v58
	v_add_f32_e32 v59, 1.0, v59
	v_mul_f32_e32 v36, 0xbfb8aa3b, v36
	v_add_f32_e32 v122, 1.0, v54
	v_add_f32_e32 v123, 1.0, v55
	v_rcp_f32_e32 v54, v56
	v_rcp_f32_e32 v55, v57
	v_rcp_f32_e32 v56, v58
	v_rcp_f32_e32 v57, v59
	v_exp_f32_e32 v36, v36
	v_add_f32_e32 v62, 1.0, v62
	v_add_f32_e32 v63, 1.0, v52
	v_mul_f32_e32 v46, 0xbfb8aa3b, v46
	v_mul_f32_e32 v47, 0xbfb8aa3b, v47
	v_add_f32_e32 v121, 1.0, v53
	v_rcp_f32_e32 v53, v62
	v_rcp_f32_e32 v120, v63
	v_exp_f32_e32 v46, v46
	v_exp_f32_e32 v47, v47
	v_mul_f32_e32 v42, 0xbfb8aa3b, v42
	v_mul_f32_e32 v43, 0xbfb8aa3b, v43
	v_exp_f32_e32 v42, v42
	v_exp_f32_e32 v43, v43
	v_mul_f32_e32 v48, 0xbfb8aa3b, v48
	v_exp_f32_e32 v48, v48
	v_add_f32_e32 v61, 1.0, v61
	v_rcp_f32_e32 v52, v61
	v_rcp_f32_e32 v121, v121
	v_add_f32_e32 v46, 1.0, v46
	v_add_f32_e32 v47, 1.0, v47
	v_rcp_f32_e32 v46, v46
	v_rcp_f32_e32 v47, v47
	v_add_f32_e32 v42, 1.0, v42
	v_add_f32_e32 v43, 1.0, v43
	v_mul_f32_e32 v32, 0xbfb8aa3b, v32
	v_add_f32_e32 v49, 1.0, v49
	v_add_f32_e32 v60, 1.0, v60
	v_rcp_f32_e32 v42, v42
	v_rcp_f32_e32 v43, v43
	v_exp_f32_e32 v32, v32
	v_add_f32_e32 v126, 1.0, v48
	v_rcp_f32_e32 v48, v49
	v_rcp_f32_e32 v49, v60
	v_mul_f32_e32 v44, 0xbfb8aa3b, v44
	v_mul_f32_e32 v45, 0xbfb8aa3b, v45
	v_exp_f32_e32 v44, v44
	s_waitcnt vmcnt(7)
	v_lshlrev_b32_e32 v60, 16, v106
	s_waitcnt vmcnt(6)
	v_lshlrev_b32_e32 v62, 16, v109
	v_and_b32_e32 v63, 0xffff0000, v109
	v_pk_mul_f32 v[62:63], v[56:57], v[62:63]
	v_exp_f32_e32 v57, v105
	v_add_f32_e32 v105, 1.0, v36
	v_mul_f32_e32 v36, 0xbfb8aa3b, v37
	v_mul_f32_e32 v37, 0xbfb8aa3b, v38
	v_mul_f32_e32 v38, 0xbfb8aa3b, v39
	v_exp_f32_e32 v37, v37
	v_exp_f32_e32 v38, v38
	v_exp_f32_e32 v39, v36
	v_and_b32_e32 v61, 0xffff0000, v106
	v_add_f32_e32 v36, 1.0, v37
	v_add_f32_e32 v37, 1.0, v38
	v_lshlrev_b32_e32 v58, 16, v107
	v_and_b32_e32 v59, 0xffff0000, v107
	v_lshlrev_b32_e32 v106, 16, v108
	v_and_b32_e32 v107, 0xffff0000, v108
	s_waitcnt vmcnt(5)
	v_lshlrev_b32_e32 v108, 16, v110
	v_and_b32_e32 v109, 0xffff0000, v110
	v_rcp_f32_e32 v36, v36
	v_rcp_f32_e32 v37, v37
	v_pk_mul_f32 v[58:59], v[52:53], v[58:59]
	v_pk_mul_f32 v[52:53], v[120:121], v[108:109]
	s_waitcnt vmcnt(3)
	v_lshlrev_b32_e32 v108, 16, v115
	v_and_b32_e32 v109, 0xffff0000, v115
	v_exp_f32_e32 v45, v45
	v_pk_mul_f32 v[46:47], v[46:47], v[108:109]
	v_mul_f32_e32 v40, 0xbfb8aa3b, v40
	v_mul_f32_e32 v41, 0xbfb8aa3b, v41
	s_waitcnt vmcnt(2)
	v_lshlrev_b32_e32 v108, 16, v117
	v_and_b32_e32 v109, 0xffff0000, v117
	v_exp_f32_e32 v40, v40
	v_exp_f32_e32 v41, v41
	v_pk_mul_f32 v[42:43], v[42:43], v[108:109]
	s_waitcnt vmcnt(1)
; #define GAS __attribute__((address_space(1)))
; __device__ __forceinline__ float bflo(unsigned w) { return __uint_as_float(w << 16); }
; __device__ __forceinline__ float bfhi(unsigned w) { return __uint_as_float(w & 0xffff0000u); }
; __device__ __forceinline__ float sigmf(float x) { return __builtin_amdgcn_rcpf(1.0f + __expf(-x)); }
; __device__ __forceinline__ float dot4(f32x4 a, f32x4 b) { return (a[0] * b[0] + a[1] * b[1]) + (a[2] * b[2] + a[3] * b[3]); }
;     ...
;                 if (TSRC == 2) { const GAS v2u* pp = (const GAS v2u*)(PUP + (size_t)r * D) + lane;
; #pragma unroll
;                     for (int j = 0; j < 8; ++j) { const v2u pw = pp[64 * j]; const f32x4 p = (f32x4){bflo(pw.x), bfhi(pw.x), bflo(pw.y), bfhi(pw.y)}; t[j] = (f32x4){sigmf(t[j][0]), sigmf(t[j][1]), sigmf(t[j][2]), sigmf(t[j][3])} * p; } }
; #pragma unroll
;                 for (int j = 0; j < 8; ++j) ss += dot4(t[j], t[j]);
	v_lshlrev_b32_e32 v108, 16, v119
	v_and_b32_e32 v109, 0xffff0000, v119
	v_add_f32_e32 v32, 1.0, v32
	v_pk_mul_f32 v[36:37], v[36:37], v[108:109]
	v_rcp_f32_e32 v108, v32
	v_mul_f32_e32 v32, 0xbfb8aa3b, v33
	v_mul_f32_e32 v33, 0xbfb8aa3b, v34
	v_mul_f32_e32 v34, 0xbfb8aa3b, v35
	v_exp_f32_e32 v32, v32
	v_exp_f32_e32 v33, v33
	v_exp_f32_e32 v34, v34
	v_add_f32_e32 v44, 1.0, v44
	v_add_f32_e32 v45, 1.0, v45
	v_rcp_f32_e32 v44, v44
	v_rcp_f32_e32 v45, v45
	v_add_f32_e32 v40, 1.0, v40
	v_add_f32_e32 v41, 1.0, v41
	v_rcp_f32_e32 v40, v40
	v_rcp_f32_e32 v41, v41
	v_add_f32_e32 v39, 1.0, v39
	v_rcp_f32_e32 v38, v105
	v_rcp_f32_e32 v39, v39
	v_add_f32_e32 v35, 1.0, v32
	v_add_f32_e32 v32, 1.0, v33
	v_add_f32_e32 v33, 1.0, v34
	v_pk_mul_f32 v[54:55], v[54:55], v[106:107]
	v_lshlrev_b32_e32 v106, 16, v114
	v_and_b32_e32 v107, 0xffff0000, v114
	v_rcp_f32_e32 v32, v32
	v_rcp_f32_e32 v33, v33
	v_rcp_f32_e32 v109, v35
	v_pk_mul_f32 v[44:45], v[44:45], v[106:107]
	v_lshlrev_b32_e32 v106, 16, v116
	v_and_b32_e32 v107, 0xffff0000, v116
	v_pk_mul_f32 v[40:41], v[40:41], v[106:107]
	v_lshlrev_b32_e32 v106, 16, v118
	v_and_b32_e32 v107, 0xffff0000, v118
	v_mul_f32_e32 v50, 0xbfb8aa3b, v50
	v_rcp_f32_e32 v122, v122
	v_rcp_f32_e32 v123, v123
	v_pk_mul_f32 v[60:61], v[48:49], v[60:61]
	v_mul_f32_e32 v51, 0xbfb8aa3b, v51
	v_pk_mul_f32 v[38:39], v[38:39], v[106:107]
	s_waitcnt vmcnt(0)
	v_lshlrev_b32_e32 v106, 16, v90
	v_and_b32_e32 v107, 0xffff0000, v90
	v_lshlrev_b32_e32 v34, 16, v91
	v_and_b32_e32 v35, 0xffff0000, v91
	v_exp_f32_e32 v50, v50
	v_exp_f32_e32 v51, v51
	v_pk_mul_f32 v[32:33], v[32:33], v[34:35]
	v_pk_mul_f32 v[34:35], v[108:109], v[106:107]
	v_mov_b32_e32 v106, v61
	v_mov_b32_e32 v107, v55
	v_mov_b32_e32 v90, v60
	v_mov_b32_e32 v91, v54
	v_pk_mul_f32 v[106:107], v[106:107], v[106:107]
	v_mov_b32_e32 v108, v59
	v_mov_b32_e32 v109, v63
	v_lshlrev_b32_e32 v110, 16, v111
	v_and_b32_e32 v111, 0xffff0000, v111
	v_pk_fma_f32 v[90:91], v[90:91], v[90:91], v[106:107]
	v_mov_b32_e32 v106, v58
	v_mov_b32_e32 v107, v62
	v_pk_mul_f32 v[108:109], v[108:109], v[108:109]
	v_pk_mul_f32 v[48:49], v[122:123], v[110:111]
	v_add_f32_e32 v57, 1.0, v57
	v_pk_fma_f32 v[106:107], v[106:107], v[106:107], v[108:109]
	v_add_f32_e32 v50, 1.0, v50
	v_add_f32_e32 v51, 1.0, v51
	v_rcp_f32_e32 v56, v126
	v_rcp_f32_e32 v57, v57
	v_pk_add_f32 v[90:91], v[90:91], v[106:107]
	v_pk_mul_f32 v[106:107], v[48:49], v[48:49]
	v_pk_mul_f32 v[108:109], v[52:53], v[52:53]
	v_rcp_f32_e32 v50, v50
	v_rcp_f32_e32 v51, v51
	v_pk_mov_b32 v[110:111], v[108:109], v[106:107] op_sel:[1,0]
	v_mov_b32_e32 v109, v107
	v_pk_add_f32 v[106:107], v[110:111], v[108:109]
	v_lshlrev_b32_e32 v124, 16, v112
	v_and_b32_e32 v125, 0xffff0000, v112
	v_mul_f32_e32 v105, v44, v44
	v_mul_f32_e32 v108, v45, v45
	v_pk_add_f32 v[90:91], v[90:91], v[90:91] op_sel:[0,1] op_sel_hi:[1,0]
	v_pk_add_f32 v[106:107], v[106:107], v[106:107] op_sel:[0,1] op_sel_hi:[1,0]
	v_lshlrev_b32_e32 v112, 16, v113
	v_and_b32_e32 v113, 0xffff0000, v113
	v_pk_mul_f32 v[56:57], v[56:57], v[124:125]
	v_mov_b32_e32 v91, v105
	v_mov_b32_e32 v107, v108
	v_pk_mul_f32 v[50:51], v[50:51], v[112:113]
	v_pk_add_f32 v[90:91], v[90:91], v[106:107]
	v_mul_f32_e32 v106, v57, v57
	v_mul_f32_e32 v109, v46, v46
	v_pk_fma_f32 v[106:107], v[56:57], v[56:57], v[106:107] op_sel_hi:[1,1,0]
	v_mul_f32_e32 v108, v51, v51
	v_mul_f32_e32 v110, v47, v47
	v_mov_b32_e32 v107, v109
	v_pk_fma_f32 v[108:109], v[50:51], v[50:51], v[108:109] op_sel_hi:[1,1,0]
	v_mul_f32_e32 v105, v34, v34
	v_mov_b32_e32 v109, v110
	v_pk_add_f32 v[106:107], v[106:107], v[108:109]
	v_pk_mul_f32 v[108:109], v[40:41], v[40:41]
	v_pk_add_f32 v[90:91], v[90:91], v[106:107]
	v_pk_mul_f32 v[106:107], v[42:43], v[42:43]
	v_pk_add_f32 v[90:91], v[90:91], v[90:91] op_sel:[0,1] op_sel_hi:[1,0]
	v_pk_mov_b32 v[110:111], v[108:109], v[106:107] op_sel:[1,0]
	v_mov_b32_e32 v109, v107
	v_pk_add_f32 v[106:107], v[110:111], v[108:109]
	v_mul_f32_e32 v108, v35, v35
	v_pk_add_f32 v[106:107], v[106:107], v[106:107] op_sel:[0,1] op_sel_hi:[1,0]
	v_mov_b32_e32 v91, v105
	v_mov_b32_e32 v107, v108
	v_pk_add_f32 v[90:91], v[90:91], v[106:107]
	v_mul_f32_e32 v106, v39, v39
	v_mul_f32_e32 v109, v32, v32
	v_pk_fma_f32 v[106:107], v[38:39], v[38:39], v[106:107] op_sel_hi:[1,1,0]
	v_mul_f32_e32 v108, v37, v37
	v_mul_f32_e32 v110, v33, v33
	v_mov_b32_e32 v107, v109
	v_pk_fma_f32 v[108:109], v[36:37], v[36:37], v[108:109] op_sel_hi:[1,1,0]
	s_nop 0
	v_mov_b32_e32 v109, v110
	v_pk_add_f32 v[106:107], v[106:107], v[108:109]
	s_nop 0
	v_pk_add_f32 v[90:91], v[90:91], v[106:107]
	s_nop 0
	v_add_f32_e32 v90, v90, v91
	s_branch .LBB0_1898
